# phase-0 row pass (x -> bf16 normed copy) software-pipelined with the norm gains kept in registers
# baseline (speedup 1.0000x reference)
; __device__ __forceinline__ u32x4 pack8(f32x4 a, f32x4 b) { u32x4 r; r[0] = cvt_pk_bf16(a[0], a[1]); r[1] = cvt_pk_bf16(a[2], a[3]); r[2] = cvt_pk_bf16(b[0], b[1]); r[3] = cvt_pk_bf16(b[2], b[3]); return r; }
; __device__ __forceinline__ void rowpass(int wv, const float* xin, const bf16_t* outb, const float* g_post, const float* g_pre_next, float* xres, bf16_t* xn, int mode) { LIDS
;     ...
;     for (int row = bid_l * 8 + wid; row < SEQ; row += gdim_l * 8) {
;         f32x4 xv[8]; float ss = 0.f;
;         if (mode == 0) {
; #pragma unroll
;             for (int i = 0; i < 8; ++i) xv[i] = __builtin_nontemporal_load((const f32x4*)(xin + (size_t)row * DM + RP_OFF(i)));
;     ...
;         if (g_pre_next) {
;             ss = wave_sum(ss); const float inv = rsqrtf(ss * (1.0f / DM) + EPS);
; #pragma unroll
;             for (int ip = 0; ip < 4; ++ip) { const f32x4 g0 = *(const f32x4*)(g_pre_next + RP_OFF(2 * ip)), g1 = *(const f32x4*)(g_pre_next + RP_OFF(2 * ip + 1));
;                 const f32x4 y0 = xv[2 * ip] * inv * g0, y1 = xv[2 * ip + 1] * inv * g1;
;                 *(u32x4*)(xn + (size_t)row * DM + ip * 512 + lane * 8) = pack8(y0, y1); }
.LBB0_542:
	s_andn2_b64 vcc, exec, s[14:15]
	s_cbranch_vccnz .Lr0_done
	v_xor_b32_e32 v179, 32, v216
	v_lshlrev_b32_e32 v179, 2, v179
	v_xor_b32_e32 v180, 16, v216
	v_lshlrev_b32_e32 v180, 2, v180
	v_xor_b32_e32 v181, 8, v216
	v_lshlrev_b32_e32 v181, 2, v181
	v_xor_b32_e32 v182, 4, v216
	v_lshlrev_b32_e32 v182, 2, v182
	v_xor_b32_e32 v183, 2, v216
	v_lshlrev_b32_e32 v183, 2, v183
	v_xor_b32_e32 v184, 1, v216
	v_lshlrev_b32_e32 v184, 2, v184
	global_load_dwordx4 v[138:141], v[20:21], off
	global_load_dwordx4 v[142:145], v[20:21], off offset:16
	global_load_dwordx4 v[146:149], v[20:21], off offset:2048
	global_load_dwordx4 v[150:153], v[20:21], off offset:2064
	global_load_dwordx4 v[154:157], v[22:23], off
	global_load_dwordx4 v[158:161], v[22:23], off offset:16
	global_load_dwordx4 v[162:165], v[24:25], off
	global_load_dwordx4 v[166:169], v[24:25], off offset:16
	v_readfirstlane_b32 s62, v30
	global_load_dwordx4 v[74:77], v[26:27], off offset:-4096 nt
	global_load_dwordx4 v[78:81], v[26:27], off offset:-4080 nt
	global_load_dwordx4 v[82:85], v[26:27], off offset:-2048 nt
	global_load_dwordx4 v[86:89], v[26:27], off offset:-2032 nt
	global_load_dwordx4 v[90:93], v[26:27], off nt
	global_load_dwordx4 v[94:97], v[26:27], off offset:16 nt
	global_load_dwordx4 v[98:101], v[26:27], off offset:2048 nt
	global_load_dwordx4 v[102:105], v[26:27], off offset:2064 nt
	s_mov_b32 s63, 1
.Lr0_loop:
	s_add_i32 s62, s62, s8
	s_cmp_gt_i32 s62, s96
	s_cbranch_scc1 .Lr0_last1
	v_lshl_add_u64 v[26:27], v[26:27], 0, s[10:11]
	global_load_dwordx4 v[106:109], v[26:27], off offset:-4096 nt
	global_load_dwordx4 v[110:113], v[26:27], off offset:-4080 nt
	global_load_dwordx4 v[114:117], v[26:27], off offset:-2048 nt
	global_load_dwordx4 v[118:121], v[26:27], off offset:-2032 nt
	global_load_dwordx4 v[122:125], v[26:27], off nt
	global_load_dwordx4 v[126:129], v[26:27], off offset:16 nt
	global_load_dwordx4 v[130:133], v[26:27], off offset:2048 nt
	global_load_dwordx4 v[134:137], v[26:27], off offset:2064 nt
	s_cmp_lg_u32 s63, 0
	s_cbranch_scc1 .Lr0_f1
	s_waitcnt vmcnt(12)
	s_branch .Lr0_go1
.Lr0_f1:
	s_waitcnt vmcnt(8)
	s_branch .Lr0_go1
.Lr0_last1:
	s_cmp_lg_u32 s63, 0
	s_cbranch_scc1 .Lr0_lf1
	s_waitcnt vmcnt(4)
	s_branch .Lr0_go1

; __device__ __forceinline__ u32x4 pack8(f32x4 a, f32x4 b) { u32x4 r; r[0] = cvt_pk_bf16(a[0], a[1]); r[1] = cvt_pk_bf16(a[2], a[3]); r[2] = cvt_pk_bf16(b[0], b[1]); r[3] = cvt_pk_bf16(b[2], b[3]); return r; }
; __device__ __forceinline__ float wave_sum(float v) {
;     ...
;     for (int o = 32; o >= 1; o >>= 1) v += __shfl_xor(v, o);
; __device__ __forceinline__ void rowpass(int wv, const float* xin, const bf16_t* outb, const float* g_post, const float* g_pre_next, float* xres, bf16_t* xn, int mode) { LIDS
;     ...
; #pragma unroll
;         for (int i = 0; i < 8; ++i) { if (mode != 0) __builtin_nontemporal_store(xv[i], (f32x4*)(xres + (size_t)row * DM + RP_OFF(i)));
;             ss += xv[i][0] * xv[i][0] + xv[i][1] * xv[i][1] + xv[i][2] * xv[i][2] + xv[i][3] * xv[i][3]; }
;         if (g_pre_next) {
;             ss = wave_sum(ss); const float inv = rsqrtf(ss * (1.0f / DM) + EPS);
; #pragma unroll
;             for (int ip = 0; ip < 4; ++ip) { const f32x4 g0 = *(const f32x4*)(g_pre_next + RP_OFF(2 * ip)), g1 = *(const f32x4*)(g_pre_next + RP_OFF(2 * ip + 1));
;                 const f32x4 y0 = xv[2 * ip] * inv * g0, y1 = xv[2 * ip + 1] * inv * g1;
;                 *(u32x4*)(xn + (size_t)row * DM + ip * 512 + lane * 8) = pack8(y0, y1); }
.Lr0_go1:
	s_mov_b32 s63, 0
	v_mul_f32_e32 v170, v74, v74
	v_mul_f32_e32 v171, v75, v75
	v_mul_f32_e32 v172, v76, v76
	v_mul_f32_e32 v173, v77, v77
	v_fmac_f32_e32 v170, v78, v78
	v_fmac_f32_e32 v171, v79, v79
	v_fmac_f32_e32 v172, v80, v80
	v_fmac_f32_e32 v173, v81, v81
	v_fmac_f32_e32 v170, v82, v82
	v_fmac_f32_e32 v171, v83, v83
	v_fmac_f32_e32 v172, v84, v84
	v_fmac_f32_e32 v173, v85, v85
	v_fmac_f32_e32 v170, v86, v86
	v_fmac_f32_e32 v171, v87, v87
	v_fmac_f32_e32 v172, v88, v88
	v_fmac_f32_e32 v173, v89, v89
	v_fmac_f32_e32 v170, v90, v90
	v_fmac_f32_e32 v171, v91, v91
	v_fmac_f32_e32 v172, v92, v92
	v_fmac_f32_e32 v173, v93, v93
	v_fmac_f32_e32 v170, v94, v94
	v_fmac_f32_e32 v171, v95, v95
	v_fmac_f32_e32 v172, v96, v96
	v_fmac_f32_e32 v173, v97, v97
	v_fmac_f32_e32 v170, v98, v98
	v_fmac_f32_e32 v171, v99, v99
	v_fmac_f32_e32 v172, v100, v100
	v_fmac_f32_e32 v173, v101, v101
	v_fmac_f32_e32 v170, v102, v102
	v_fmac_f32_e32 v171, v103, v103
	v_fmac_f32_e32 v172, v104, v104
	v_fmac_f32_e32 v173, v105, v105
	v_add_f32_e32 v170, v170, v171
	v_add_f32_e32 v172, v172, v173
	v_add_f32_e32 v174, v170, v172
	ds_bpermute_b32 v175, v179, v174
	s_waitcnt lgkmcnt(0)
	v_add_f32_e32 v174, v174, v175
	ds_bpermute_b32 v175, v180, v174
	s_waitcnt lgkmcnt(0)
	v_add_f32_e32 v174, v174, v175
	ds_bpermute_b32 v175, v181, v174
	s_waitcnt lgkmcnt(0)
	v_add_f32_e32 v174, v174, v175
	ds_bpermute_b32 v175, v182, v174
	s_waitcnt lgkmcnt(0)
	v_add_f32_e32 v174, v174, v175
	ds_bpermute_b32 v175, v183, v174
	s_waitcnt lgkmcnt(0)
	v_add_f32_e32 v174, v174, v175
	ds_bpermute_b32 v175, v184, v174
	s_waitcnt lgkmcnt(0)
	v_add_f32_e32 v174, v174, v175
	v_fmamk_f32 v178, v174, 0x3a000000, v252
	v_rsq_f32_e32 v178, v178
	s_nop 0
	v_mul_f32_e32 v186, v74, v178
	v_mul_f32_e32 v187, v75, v178
	v_mul_f32_e32 v188, v76, v178
	v_mul_f32_e32 v189, v77, v178
	v_mul_f32_e32 v190, v78, v178
	v_mul_f32_e32 v191, v79, v178
	v_mul_f32_e32 v192, v80, v178
	v_mul_f32_e32 v193, v81, v178
	v_mul_f32_e32 v186, v186, v138
	v_mul_f32_e32 v187, v187, v139
	v_mul_f32_e32 v188, v188, v140
	v_mul_f32_e32 v189, v189, v141
	v_mul_f32_e32 v190, v190, v142
	v_mul_f32_e32 v191, v191, v143
	v_mul_f32_e32 v192, v192, v144
	v_mul_f32_e32 v193, v193, v145
	v_cvt_pk_bf16_f32 v194, v186, v187
	v_cvt_pk_bf16_f32 v195, v188, v189
	v_cvt_pk_bf16_f32 v196, v190, v191
	v_cvt_pk_bf16_f32 v197, v192, v193
	global_store_dwordx4 v[28:29], v[194:197], off offset:-3072
	v_mul_f32_e32 v186, v82, v178
	v_mul_f32_e32 v187, v83, v178
	v_mul_f32_e32 v188, v84, v178
	v_mul_f32_e32 v189, v85, v178
	v_mul_f32_e32 v190, v86, v178
	v_mul_f32_e32 v191, v87, v178
	v_mul_f32_e32 v192, v88, v178
	v_mul_f32_e32 v193, v89, v178
	v_mul_f32_e32 v186, v186, v146
	v_mul_f32_e32 v187, v187, v147
	v_mul_f32_e32 v188, v188, v148
	v_mul_f32_e32 v189, v189, v149
	v_mul_f32_e32 v190, v190, v150
	v_mul_f32_e32 v191, v191, v151
	v_mul_f32_e32 v192, v192, v152
	v_mul_f32_e32 v193, v193, v153
	v_cvt_pk_bf16_f32 v194, v186, v187
	v_cvt_pk_bf16_f32 v195, v188, v189
	v_cvt_pk_bf16_f32 v196, v190, v191
	v_cvt_pk_bf16_f32 v197, v192, v193
	global_store_dwordx4 v[28:29], v[194:197], off offset:-2048
	v_mul_f32_e32 v186, v90, v178
	v_mul_f32_e32 v187, v91, v178
	v_mul_f32_e32 v188, v92, v178
	v_mul_f32_e32 v189, v93, v178
	v_mul_f32_e32 v190, v94, v178
	v_mul_f32_e32 v191, v95, v178
	v_mul_f32_e32 v192, v96, v178
	v_mul_f32_e32 v193, v97, v178
	v_mul_f32_e32 v186, v186, v154
	v_mul_f32_e32 v187, v187, v155
	v_mul_f32_e32 v188, v188, v156
	v_mul_f32_e32 v189, v189, v157
	v_mul_f32_e32 v190, v190, v158
	v_mul_f32_e32 v191, v191, v159
	v_mul_f32_e32 v192, v192, v160
	v_mul_f32_e32 v193, v193, v161
	v_cvt_pk_bf16_f32 v194, v186, v187
	v_cvt_pk_bf16_f32 v195, v188, v189
	v_cvt_pk_bf16_f32 v196, v190, v191
	v_cvt_pk_bf16_f32 v197, v192, v193
	global_store_dwordx4 v[28:29], v[194:197], off offset:-1024
	v_mul_f32_e32 v186, v98, v178
	v_mul_f32_e32 v187, v99, v178
	v_mul_f32_e32 v188, v100, v178
	v_mul_f32_e32 v189, v101, v178
	v_mul_f32_e32 v190, v102, v178
	v_mul_f32_e32 v191, v103, v178
	v_mul_f32_e32 v192, v104, v178
	v_mul_f32_e32 v193, v105, v178
	v_mul_f32_e32 v186, v186, v162
	v_mul_f32_e32 v187, v187, v163
	v_mul_f32_e32 v188, v188, v164
	v_mul_f32_e32 v189, v189, v165
	v_mul_f32_e32 v190, v190, v166
	v_mul_f32_e32 v191, v191, v167
	v_mul_f32_e32 v192, v192, v168
	v_mul_f32_e32 v193, v193, v169
	v_cvt_pk_bf16_f32 v194, v186, v187
	v_cvt_pk_bf16_f32 v195, v188, v189
	v_cvt_pk_bf16_f32 v196, v190, v191
	v_cvt_pk_bf16_f32 v197, v192, v193
	global_store_dwordx4 v[28:29], v[194:197], off
	v_lshl_add_u64 v[28:29], v[28:29], 0, s[12:13]
	s_cmp_gt_i32 s62, s96
	s_cbranch_scc1 .Lr0_done
	s_add_i32 s62, s62, s8
	s_cmp_gt_i32 s62, s96
	s_cbranch_scc1 .Lr0_last2
	v_lshl_add_u64 v[26:27], v[26:27], 0, s[10:11]
	global_load_dwordx4 v[74:77], v[26:27], off offset:-4096 nt
	global_load_dwordx4 v[78:81], v[26:27], off offset:-4080 nt
	global_load_dwordx4 v[82:85], v[26:27], off offset:-2048 nt
	global_load_dwordx4 v[86:89], v[26:27], off offset:-2032 nt
	global_load_dwordx4 v[90:93], v[26:27], off nt
	global_load_dwordx4 v[94:97], v[26:27], off offset:16 nt
	global_load_dwordx4 v[98:101], v[26:27], off offset:2048 nt
	global_load_dwordx4 v[102:105], v[26:27], off offset:2064 nt
	s_cmp_lg_u32 s63, 0
	s_cbranch_scc1 .Lr0_f2
	s_waitcnt vmcnt(12)
	s_branch .Lr0_go2

; #define LAS __attribute__((address_space(3)))
; __device__ __forceinline__ u32x4 pack8(f32x4 a, f32x4 b) { u32x4 r; r[0] = cvt_pk_bf16(a[0], a[1]); r[1] = cvt_pk_bf16(a[2], a[3]); r[2] = cvt_pk_bf16(b[0], b[1]); r[3] = cvt_pk_bf16(b[2], b[3]); return r; }
; #define LIDS const int tid_l = TID(), bid_l = BID(), gdim_l = GDIM(); (void)tid_l; (void)bid_l; (void)gdim_l;
; __device__ __forceinline__ void rowpass(int wv, const float* xin, const bf16_t* outb, const float* g_post, const float* g_pre_next, float* xres, bf16_t* xn, int mode) { LIDS
;     ...
; #pragma unroll
;         for (int i = 0; i < 8; ++i) { if (mode != 0) __builtin_nontemporal_store(xv[i], (f32x4*)(xres + (size_t)row * DM + RP_OFF(i)));
;             ss += xv[i][0] * xv[i][0] + xv[i][1] * xv[i][1] + xv[i][2] * xv[i][2] + xv[i][3] * xv[i][3]; }
;         if (g_pre_next) {
;             ss = wave_sum(ss); const float inv = rsqrtf(ss * (1.0f / DM) + EPS);
; #pragma unroll
;             for (int ip = 0; ip < 4; ++ip) { const f32x4 g0 = *(const f32x4*)(g_pre_next + RP_OFF(2 * ip)), g1 = *(const f32x4*)(g_pre_next + RP_OFF(2 * ip + 1));
;                 const f32x4 y0 = xv[2 * ip] * inv * g0, y1 = xv[2 * ip + 1] * inv * g1;
;                 *(u32x4*)(xn + (size_t)row * DM + ip * 512 + lane * 8) = pack8(y0, y1); }
; __device__ __forceinline__ void prep_layer(int wv, const Params& p, int layer, LAS unsigned char* lds) { LIDS
;     unsigned char* ws = p.ws; LAS float* tl = (LAS float*)lds;
;     const float* w_in = p.w_in + (size_t)layer * DM * NIN_REAL; const float* w_uq = p.w_uq + (size_t)layer * 512 * 1536; const float* w_ukv = p.w_ukv + (size_t)layer * 256 * 2048;
;     const float* w_glu = p.w_glu + (size_t)layer * 1024 * 2048; const float* w_out = p.w_out + (size_t)layer * 2048 * 2048;
;     const float* g_pre = nullptr;
;     const float* g_q = p.q_norm + layer * 512; const float* g_kv = p.kv_norm + layer * 256;
;     for (int t = bid_l; t < 976; t += gdim_l) {
;         if (t < 512) transpose_tile<0>(wv, w_in, NIN_REAL, DM, g_pre, (bf16_t*)(ws + OFF_WIN), t, 8, tl);
.Lr0_go2:
	s_mov_b32 s63, 0
	v_mul_f32_e32 v170, v106, v106
	v_mul_f32_e32 v171, v107, v107
	v_mul_f32_e32 v172, v108, v108
	v_mul_f32_e32 v173, v109, v109
	v_fmac_f32_e32 v170, v110, v110
	v_fmac_f32_e32 v171, v111, v111
	v_fmac_f32_e32 v172, v112, v112
	v_fmac_f32_e32 v173, v113, v113
	v_fmac_f32_e32 v170, v114, v114
	v_fmac_f32_e32 v171, v115, v115
	v_fmac_f32_e32 v172, v116, v116
	v_fmac_f32_e32 v173, v117, v117
	v_fmac_f32_e32 v170, v118, v118
	v_fmac_f32_e32 v171, v119, v119
	v_fmac_f32_e32 v172, v120, v120
	v_fmac_f32_e32 v173, v121, v121
	v_fmac_f32_e32 v170, v122, v122
	v_fmac_f32_e32 v171, v123, v123
	v_fmac_f32_e32 v172, v124, v124
	v_fmac_f32_e32 v173, v125, v125
	v_fmac_f32_e32 v170, v126, v126
	v_fmac_f32_e32 v171, v127, v127
	v_fmac_f32_e32 v172, v128, v128
	v_fmac_f32_e32 v173, v129, v129
	v_fmac_f32_e32 v170, v130, v130
	v_fmac_f32_e32 v171, v131, v131
	v_fmac_f32_e32 v172, v132, v132
	v_fmac_f32_e32 v173, v133, v133
	v_fmac_f32_e32 v170, v134, v134
	v_fmac_f32_e32 v171, v135, v135
	v_fmac_f32_e32 v172, v136, v136
	v_fmac_f32_e32 v173, v137, v137
	v_add_f32_e32 v170, v170, v171
	v_add_f32_e32 v172, v172, v173
	v_add_f32_e32 v174, v170, v172
	ds_bpermute_b32 v175, v179, v174
	s_waitcnt lgkmcnt(0)
	v_add_f32_e32 v174, v174, v175
	ds_bpermute_b32 v175, v180, v174
	s_waitcnt lgkmcnt(0)
	v_add_f32_e32 v174, v174, v175
	ds_bpermute_b32 v175, v181, v174
	s_waitcnt lgkmcnt(0)
	v_add_f32_e32 v174, v174, v175
	ds_bpermute_b32 v175, v182, v174
	s_waitcnt lgkmcnt(0)
	v_add_f32_e32 v174, v174, v175
	ds_bpermute_b32 v175, v183, v174
	s_waitcnt lgkmcnt(0)
	v_add_f32_e32 v174, v174, v175
	ds_bpermute_b32 v175, v184, v174
	s_waitcnt lgkmcnt(0)
	v_add_f32_e32 v174, v174, v175
	v_fmamk_f32 v178, v174, 0x3a000000, v252
	v_rsq_f32_e32 v178, v178
	s_nop 0
	v_mul_f32_e32 v186, v106, v178
	v_mul_f32_e32 v187, v107, v178
	v_mul_f32_e32 v188, v108, v178
	v_mul_f32_e32 v189, v109, v178
	v_mul_f32_e32 v190, v110, v178
	v_mul_f32_e32 v191, v111, v178
	v_mul_f32_e32 v192, v112, v178
	v_mul_f32_e32 v193, v113, v178
	v_mul_f32_e32 v186, v186, v138
	v_mul_f32_e32 v187, v187, v139
	v_mul_f32_e32 v188, v188, v140
	v_mul_f32_e32 v189, v189, v141
	v_mul_f32_e32 v190, v190, v142
	v_mul_f32_e32 v191, v191, v143
	v_mul_f32_e32 v192, v192, v144
	v_mul_f32_e32 v193, v193, v145
	v_cvt_pk_bf16_f32 v194, v186, v187
	v_cvt_pk_bf16_f32 v195, v188, v189
	v_cvt_pk_bf16_f32 v196, v190, v191
	v_cvt_pk_bf16_f32 v197, v192, v193
	global_store_dwordx4 v[28:29], v[194:197], off offset:-3072
	v_mul_f32_e32 v186, v114, v178
	v_mul_f32_e32 v187, v115, v178
	v_mul_f32_e32 v188, v116, v178
	v_mul_f32_e32 v189, v117, v178
	v_mul_f32_e32 v190, v118, v178
	v_mul_f32_e32 v191, v119, v178
	v_mul_f32_e32 v192, v120, v178
	v_mul_f32_e32 v193, v121, v178
	v_mul_f32_e32 v186, v186, v146
	v_mul_f32_e32 v187, v187, v147
	v_mul_f32_e32 v188, v188, v148
	v_mul_f32_e32 v189, v189, v149
	v_mul_f32_e32 v190, v190, v150
	v_mul_f32_e32 v191, v191, v151
	v_mul_f32_e32 v192, v192, v152
	v_mul_f32_e32 v193, v193, v153
	v_cvt_pk_bf16_f32 v194, v186, v187
	v_cvt_pk_bf16_f32 v195, v188, v189
	v_cvt_pk_bf16_f32 v196, v190, v191
	v_cvt_pk_bf16_f32 v197, v192, v193
	global_store_dwordx4 v[28:29], v[194:197], off offset:-2048
	v_mul_f32_e32 v186, v122, v178
	v_mul_f32_e32 v187, v123, v178
	v_mul_f32_e32 v188, v124, v178
	v_mul_f32_e32 v189, v125, v178
	v_mul_f32_e32 v190, v126, v178
	v_mul_f32_e32 v191, v127, v178
	v_mul_f32_e32 v192, v128, v178
	v_mul_f32_e32 v193, v129, v178
	v_mul_f32_e32 v186, v186, v154
	v_mul_f32_e32 v187, v187, v155
	v_mul_f32_e32 v188, v188, v156
	v_mul_f32_e32 v189, v189, v157
	v_mul_f32_e32 v190, v190, v158
	v_mul_f32_e32 v191, v191, v159
	v_mul_f32_e32 v192, v192, v160
	v_mul_f32_e32 v193, v193, v161
	v_cvt_pk_bf16_f32 v194, v186, v187
	v_cvt_pk_bf16_f32 v195, v188, v189
	v_cvt_pk_bf16_f32 v196, v190, v191
	v_cvt_pk_bf16_f32 v197, v192, v193
	global_store_dwordx4 v[28:29], v[194:197], off offset:-1024
	v_mul_f32_e32 v186, v130, v178
	v_mul_f32_e32 v187, v131, v178
	v_mul_f32_e32 v188, v132, v178
	v_mul_f32_e32 v189, v133, v178
	v_mul_f32_e32 v190, v134, v178
	v_mul_f32_e32 v191, v135, v178
	v_mul_f32_e32 v192, v136, v178
	v_mul_f32_e32 v193, v137, v178
	v_mul_f32_e32 v186, v186, v162
	v_mul_f32_e32 v187, v187, v163
	v_mul_f32_e32 v188, v188, v164
	v_mul_f32_e32 v189, v189, v165
	v_mul_f32_e32 v190, v190, v166
	v_mul_f32_e32 v191, v191, v167
	v_mul_f32_e32 v192, v192, v168
	v_mul_f32_e32 v193, v193, v169
	v_cvt_pk_bf16_f32 v194, v186, v187
	v_cvt_pk_bf16_f32 v195, v188, v189
	v_cvt_pk_bf16_f32 v196, v190, v191
	v_cvt_pk_bf16_f32 v197, v192, v193
	global_store_dwordx4 v[28:29], v[194:197], off
	v_lshl_add_u64 v[28:29], v[28:29], 0, s[12:13]
	s_cmp_gt_i32 s62, s96
	s_cbranch_scc1 .Lr0_done
	s_branch .Lr0_loop
.Lr0_done:
.LBB0_544:
	s_or_b64 exec, exec, s[4:5]
	s_mov_b32 s0, s3
	s_mov_b32 s8, s2
	v_mbcnt_lo_u32_b32 v0, -1, 0
	v_mbcnt_hi_u32_b32 v0, -1, v0
	s_mov_b32 s9, s56
	s_cmpk_gt_i32 s8, 0x3cf
	s_cbranch_scc1 .LBB0_499
	s_lshl_b32 s0, s8, 3
	s_add_i32 s12, s0, 0xffffe980
	s_lshl_b32 s0, s8, 4
	s_add_i32 s55, s0, 0xffffdb00
	s_lshl_b32 s0, s8, 7
	s_add_i32 s59, s0, 0xfffee000
	s_lshl_b32 s4, s8, 6
	s_add_i32 s69, s0, 0xfffee800
	s_lshl_b32 s0, s8, 5
	v_readlane_b32 s20, v253, 22
	v_readlane_b32 s22, v253, 24
	v_readlane_b32 s24, v253, 26
	s_lshl_b32 s10, s8, 8
	s_lshl_b32 s11, s9, 8
	s_lshl_b32 s13, s9, 3
	s_lshl_b32 s58, s9, 4
	s_lshl_b32 s62, s9, 7
	s_add_i32 s63, s4, 0xffff7000
	s_lshl_b32 s68, s9, 6
	s_add_i32 s72, s0, 0xffffc000
	s_lshl_b32 s73, s9, 5
	v_readlane_b32 s21, v253, 23
	v_readlane_b32 s23, v253, 25
	v_readlane_b32 s25, v253, 27
	s_mov_b32 s26, 0x10000
	s_branch .LBB0_548
